# NSA select/window attention: wave halves take the per-tile barrier at different points of the iteration (half-iteration stagger: one half's softmax beside the other half's MFMAs)
# baseline (speedup 1.0000x reference)
; #define LAS __attribute__((address_space(3)))
; template <int MODE>
; __device__ __forceinline__ void attn_pass(LAS unsigned char* lds, const bf16_t* base, int gk, int q0, const float* relb_b, const unsigned* selrow, f32x4 (&o)[2][4]) {
;     ...
;     const int tid = tid_, lane = tid & 63, wid = __builtin_amdgcn_readfirstlane(tid >> 6), c = lane & 15, g = lane >> 4;
;     constexpr int W = (MODE == MODE_BWIN) ? 512 : 1 << 20;
;     constexpr float LOG2E = 1.4426950408889634f, C1 = 0.125f * LOG2E;
;     const int hh = wid & 3, h = gk * 4 + hh;
;     const bf16_t* qp = base + C_BQ + h * 64;
;     const bf16_t* kp = base + (MODE == MODE_BSLC ? C_BKS : C_BKW) + gk * 64;
;     const bf16_t* vp = base + (MODE == MODE_BSLC ? C_BVS : C_BVW) + gk * 64;
;     LAS float* lutw = (LAS float*)(lds + ATT_LUT);
;     const LAS float* lut = lutw + hh * 128;
;     const int qw0 = q0 + (wid >> 2) * 32;
.Lattb_stag:
	v_readfirstlane_b32 s6, v214
	s_nop 3
	s_lshr_b32 s6, s6, 8
	s_and_b32 s6, s6, 1
	s_mov_b32 m0, s6
	s_branch .LBB0_49

; #define LAS __attribute__((address_space(3)))
; #define MFMA16(a, b, c) __builtin_amdgcn_mfma_f32_16x16x32_bf16((a), (b), (c), 0, 0, 0)
; __device__ __forceinline__ bf16x8 vfrag(const LAS unsigned char* p) { const v4i16_t a = tr_read(p), b = tr_read(p + 16 * KPB); return (bf16x8){a[0], a[1], a[2], a[3], b[0], b[1], b[2], b[3]}; }
; template <int MODE>
; __device__ __forceinline__ void attn_pass(LAS unsigned char* lds, const bf16_t* base, int gk, int q0, const float* relb_b, const unsigned* selrow, f32x4 (&o)[2][4]) {
;     ...
;         const bool need = (MODE == MODE_BSLC) ? (((selw >> kb) & 1u) != 0u) : true;
;         if (need) {
;         bf16x8 kfr[4][2], vfr[4][2];
; #pragma unroll
;         for (int nt = 0; nt < 4; ++nt) { kfr[nt][0] = *(const LAS bf16x8*)(Ks + (16 * nt + c) * KPB + g * 16); kfr[nt][1] = *(const LAS bf16x8*)(Ks + (16 * nt + c) * KPB + 64 + g * 16); }
;         { const LAS unsigned char* vb = Vs + (4 * g + (c >> 2)) * KPB + (c & 3) * 8;
; #pragma unroll
;           for (int dt = 0; dt < 4; ++dt)
; #pragma unroll
;             for (int p = 0; p < 2; ++p) vfr[dt][p] = vfrag(vb + 32 * p * KPB + dt * 32); }
;         __builtin_amdgcn_sched_barrier(0);
;         f32x4 s[2][4];
; #pragma unroll
;         for (int nt = 0; nt < 4; ++nt) {
; #pragma unroll
;             for (int qt = 0; qt < 2; ++qt) { f32x4 z = (f32x4){0.f, 0.f, 0.f, 0.f}; z = MFMA16(kfr[nt][0], qf[qt][0], z); s[qt][nt] = MFMA16(kfr[nt][1], qf[qt][1], z); }
;         }
;         const bool far = (qw0 - (k0 + 63)) >= 113;
;         const bool fast = far && ((qw0 + 31 - k0) < W);
.LBB0_62:
	s_lshl_b32 s52, 1, s10
	s_and_b32 s0, s52, s44
	s_cmp_eq_u32 s0, 0
	s_cbranch_scc1 .LBB0_72
	s_mul_i32 s0, s50, 0x2400
	v_add_u32_e32 v2, s0, v153
	ds_read_b128 v[96:99], v2
	ds_read_b128 v[100:103], v2 offset:64
	ds_read_b128 v[104:107], v2 offset:2304
	ds_read_b128 v[112:115], v2 offset:2368
	ds_read_b128 v[116:119], v2 offset:4608
	ds_read_b128 v[120:123], v2 offset:4672
	ds_read_b128 v[124:127], v2 offset:6912
	ds_read_b128 v[158:161], v2 offset:6976
	v_add_u32_e32 v2, s0, v151
	ds_read_b64_tr_b16 v[92:93], v2 offset:18432
	ds_read_b64_tr_b16 v[84:85], v2 offset:18464
	ds_read_b64_tr_b16 v[76:77], v2 offset:18496
	ds_read_b64_tr_b16 v[68:69], v2 offset:18528
	ds_read_b64_tr_b16 v[94:95], v2 offset:20736
	ds_read_b64_tr_b16 v[86:87], v2 offset:20768
	ds_read_b64_tr_b16 v[78:79], v2 offset:20800
	ds_read_b64_tr_b16 v[70:71], v2 offset:20832
	ds_read_b64_tr_b16 v[88:89], v2 offset:23040
	ds_read_b64_tr_b16 v[80:81], v2 offset:23072
	ds_read_b64_tr_b16 v[72:73], v2 offset:23104
	ds_read_b64_tr_b16 v[64:65], v2 offset:23136
	ds_read_b64_tr_b16 v[90:91], v2 offset:25344
	ds_read_b64_tr_b16 v[82:83], v2 offset:25376
	ds_read_b64_tr_b16 v[74:75], v2 offset:25408
	ds_read_b64_tr_b16 v[66:67], v2 offset:25440
	s_lshl_b32 s15, s10, 6
	s_waitcnt lgkmcnt(14)
	v_mfma_f32_16x16x32_bf16 v[108:111], v[96:99], v[40:43], 0
	s_sub_i32 s0, s48, s15
	s_cmpk_lt_i32 s0, 0x71
	s_cselect_b64 s[0:1], -1, 0
	v_mfma_f32_16x16x32_bf16 v[96:99], v[96:99], v[48:51], 0
	s_sub_i32 s10, s49, s15
	s_cmp_gt_i32 s10, 0xfffff
	s_cselect_b64 s[10:11], -1, 0
	v_mfma_f32_16x16x32_bf16 v[140:143], v[100:103], v[44:47], v[108:111]
	s_or_b64 s[10:11], s[0:1], s[10:11]
	v_and_b32_e32 v2, s52, v146
	v_cmp_eq_u32_e64 s[0:1], 0, v2
	v_mfma_f32_16x16x32_bf16 v[108:111], v[100:103], v[52:55], v[96:99]
	s_mov_b64 s[26:27], -1
	s_and_b64 vcc, exec, s[10:11]
	v_mfma_f32_16x16x32_bf16 v[96:99], v[104:107], v[40:43], 0
	v_mfma_f32_16x16x32_bf16 v[136:139], v[112:115], v[44:47], v[96:99]
	v_mfma_f32_16x16x32_bf16 v[96:99], v[104:107], v[48:51], 0
	v_mfma_f32_16x16x32_bf16 v[104:107], v[112:115], v[52:55], v[96:99]
	v_mfma_f32_16x16x32_bf16 v[96:99], v[116:119], v[40:43], 0
	v_mfma_f32_16x16x32_bf16 v[132:135], v[120:123], v[44:47], v[96:99]
	v_mfma_f32_16x16x32_bf16 v[96:99], v[116:119], v[48:51], 0
	v_mfma_f32_16x16x32_bf16 v[100:103], v[120:123], v[52:55], v[96:99]
	v_mfma_f32_16x16x32_bf16 v[96:99], v[124:127], v[40:43], 0
	v_mfma_f32_16x16x32_bf16 v[128:131], v[158:161], v[44:47], v[96:99]
	v_mfma_f32_16x16x32_bf16 v[96:99], v[124:127], v[48:51], 0
	v_mfma_f32_16x16x32_bf16 v[96:99], v[158:161], v[52:55], v[96:99]
	v_subrev_u32_e32 v158, s15, v152
	s_cmp_eq_u32 m0, 0
	s_cbranch_scc1 .Lstg1_mid
	s_waitcnt lgkmcnt(0)
	s_barrier
.Lstg1_mid:
	s_cbranch_vccnz .LBB0_75
	s_and_b64 vcc, exec, s[26:27]
	s_cbranch_vccnz .LBB0_108

; #define LDS_BARRIER() asm volatile("s_waitcnt lgkmcnt(0)\n\ts_barrier" ::: "memory")
; template <int MODE>
; __device__ __forceinline__ void attn_pass(LAS unsigned char* lds, const bf16_t* base, int gk, int q0, const float* relb_b, const unsigned* selrow, f32x4 (&o)[2][4]) {
;     ...
;         LDS_BARRIER();
;         kb = kbn; kbn = kbnn; buf ^= 1;
.LBB0_72:
	v_mov_b32_e32 v127, v155
	v_mov_b32_e32 v3, v157
	s_cmp_eq_u32 m0, 0
	s_cbranch_scc1 .LBB0_73
	s_waitcnt lgkmcnt(0)
	s_barrier
.LBB0_73:
	s_and_b64 s[0:1], exec, s[8:9]
	s_cselect_b32 s0, -1, s51
	s_cmp_lg_u32 m0, 0
	s_cbranch_scc1 .Lstg1_end
	s_waitcnt lgkmcnt(0)
	s_barrier
.Lstg1_end:
	s_lshl_b32 s1, 1, s0
	s_andn2_b32 s46, s46, s1
	s_andn2_b64 vcc, exec, s[6:7]
	s_xor_b32 s50, s50, 1
	s_cbranch_vccz .LBB0_143
	v_mov_b32_e32 v157, v3
	v_mov_b32_e32 v155, v127
	s_mov_b32 s10, s45
	s_mov_b32 s45, s0
	s_cmp_lt_i32 s45, 0
	s_cselect_b64 s[6:7], -1, 0
	s_and_b64 vcc, exec, s[6:7]
	s_cbranch_vccz .LBB0_59
	s_branch .LBB0_60

; #define LAS __attribute__((address_space(3)))
; #define MFMA16(a, b, c) __builtin_amdgcn_mfma_f32_16x16x32_bf16((a), (b), (c), 0, 0, 0)
; __device__ __forceinline__ bf16x8 vfrag(const LAS unsigned char* p) { const v4i16_t a = tr_read(p), b = tr_read(p + 16 * KPB); return (bf16x8){a[0], a[1], a[2], a[3], b[0], b[1], b[2], b[3]}; }
; template <int MODE>
; __device__ __forceinline__ void attn_pass(LAS unsigned char* lds, const bf16_t* base, int gk, int q0, const float* relb_b, const unsigned* selrow, f32x4 (&o)[2][4]) {
;     ...
;         if (need) {
;         bf16x8 kfr[4][2], vfr[4][2];
; #pragma unroll
;         for (int nt = 0; nt < 4; ++nt) { kfr[nt][0] = *(const LAS bf16x8*)(Ks + (16 * nt + c) * KPB + g * 16); kfr[nt][1] = *(const LAS bf16x8*)(Ks + (16 * nt + c) * KPB + 64 + g * 16); }
;         { const LAS unsigned char* vb = Vs + (4 * g + (c >> 2)) * KPB + (c & 3) * 8;
; #pragma unroll
;           for (int dt = 0; dt < 4; ++dt)
; #pragma unroll
;             for (int p = 0; p < 2; ++p) vfr[dt][p] = vfrag(vb + 32 * p * KPB + dt * 32); }
;         __builtin_amdgcn_sched_barrier(0);
;         f32x4 s[2][4];
; #pragma unroll
;         for (int nt = 0; nt < 4; ++nt) {
; #pragma unroll
;             for (int qt = 0; qt < 2; ++qt) { f32x4 z = (f32x4){0.f, 0.f, 0.f, 0.f}; z = MFMA16(kfr[nt][0], qf[qt][0], z); s[qt][nt] = MFMA16(kfr[nt][1], qf[qt][1], z); }
;         }
;         const bool far = (qw0 - (k0 + 63)) >= 113;
;         const bool fast = far && ((qw0 + 31 - k0) < W);
.LBB0_151:
	s_mul_i32 s0, s45, 0x2400
	v_add_u32_e32 v2, s0, v194
	ds_read_b128 v[128:131], v2
	ds_read_b128 v[132:135], v2 offset:64
	ds_read_b128 v[136:139], v2 offset:2304
	ds_read_b128 v[144:147], v2 offset:2368
	ds_read_b128 v[148:151], v2 offset:4608
	ds_read_b128 v[152:155], v2 offset:4672
	ds_read_b128 v[156:159], v2 offset:6912
	ds_read_b128 v[202:205], v2 offset:6976
	v_add_u32_e32 v2, s0, v190
	ds_read_b64_tr_b16 v[124:125], v2 offset:18432
	ds_read_b64_tr_b16 v[116:117], v2 offset:18464
	ds_read_b64_tr_b16 v[108:109], v2 offset:18496
	ds_read_b64_tr_b16 v[100:101], v2 offset:18528
	ds_read_b64_tr_b16 v[126:127], v2 offset:20736
	ds_read_b64_tr_b16 v[118:119], v2 offset:20768
	ds_read_b64_tr_b16 v[110:111], v2 offset:20800
	ds_read_b64_tr_b16 v[102:103], v2 offset:20832
	ds_read_b64_tr_b16 v[120:121], v2 offset:23040
	ds_read_b64_tr_b16 v[112:113], v2 offset:23072
	ds_read_b64_tr_b16 v[104:105], v2 offset:23104
	ds_read_b64_tr_b16 v[96:97], v2 offset:23136
	ds_read_b64_tr_b16 v[122:123], v2 offset:25344
	ds_read_b64_tr_b16 v[114:115], v2 offset:25376
	ds_read_b64_tr_b16 v[106:107], v2 offset:25408
	ds_read_b64_tr_b16 v[98:99], v2 offset:25440
	s_waitcnt lgkmcnt(14)
	v_mfma_f32_16x16x32_bf16 v[140:143], v[128:131], v[72:75], 0
	s_lshl_b32 s15, s10, 6
	s_sub_i32 s0, s43, s15
	s_cmpk_lt_i32 s0, 0x71
	v_mfma_f32_16x16x32_bf16 v[128:131], v[128:131], v[80:83], 0
	s_cselect_b64 s[0:1], -1, 0
	s_sub_i32 s10, s44, s15
	s_cmpk_gt_i32 s10, 0x1ff
	v_mfma_f32_16x16x32_bf16 v[172:175], v[132:135], v[76:79], v[140:143]
	s_cselect_b64 s[10:11], -1, 0
	v_subrev_u32_e32 v199, s15, v185
	s_or_b64 s[10:11], s[0:1], s[10:11]
	v_mfma_f32_16x16x32_bf16 v[140:143], v[132:135], v[84:87], v[128:131]
	v_sub_u32_e32 v198, v199, v189
	s_mov_b64 s[26:27], -1
	s_and_b64 vcc, exec, s[10:11]
	v_mfma_f32_16x16x32_bf16 v[128:131], v[136:139], v[72:75], 0
	v_cmp_gt_u32_e64 s[0:1], s33, v198
	v_mfma_f32_16x16x32_bf16 v[168:171], v[144:147], v[76:79], v[128:131]
	v_mfma_f32_16x16x32_bf16 v[128:131], v[136:139], v[80:83], 0
	v_mfma_f32_16x16x32_bf16 v[136:139], v[144:147], v[84:87], v[128:131]
	v_mfma_f32_16x16x32_bf16 v[128:131], v[148:151], v[72:75], 0
	v_mfma_f32_16x16x32_bf16 v[164:167], v[152:155], v[76:79], v[128:131]
	v_mfma_f32_16x16x32_bf16 v[128:131], v[148:151], v[80:83], 0
	v_mfma_f32_16x16x32_bf16 v[132:135], v[152:155], v[84:87], v[128:131]
	v_mfma_f32_16x16x32_bf16 v[128:131], v[156:159], v[72:75], 0
	v_mfma_f32_16x16x32_bf16 v[160:163], v[202:205], v[76:79], v[128:131]
	v_mfma_f32_16x16x32_bf16 v[128:131], v[156:159], v[80:83], 0
	v_mfma_f32_16x16x32_bf16 v[128:131], v[202:205], v[84:87], v[128:131]
	s_cmp_eq_u32 m0, 0
	s_cbranch_scc1 .Lstg2_mid
	s_waitcnt lgkmcnt(0)
	s_barrier

; __device__ __forceinline__ unsigned cvtpk(float lo, float hi) { f32x2 v = {lo, hi}; bf16x2_t b = __builtin_convertvector(v, bf16x2_t); return __builtin_bit_cast(unsigned, b); }
; #define LDS_BARRIER() asm volatile("s_waitcnt lgkmcnt(0)\n\ts_barrier" ::: "memory")
; #define MFMA16(a, b, c) __builtin_amdgcn_mfma_f32_16x16x32_bf16((a), (b), (c), 0, 0, 0)
; template <int MODE>
; __device__ __forceinline__ void attn_pass(LAS unsigned char* lds, const bf16_t* base, int gk, int q0, const float* relb_b, const unsigned* selrow, f32x4 (&o)[2][4]) {
;     ...
;             float ps = 0.f;
; #pragma unroll
;             for (int nt = 0; nt < 4; ++nt) ps += (s[qt][nt][0] + s[qt][nt][1]) + (s[qt][nt][2] + s[qt][nt][3]);
;             lrun[qt] = lrun[qt] * alpha + ps;
;             if (__any(mnew > mrun[qt])) {
; #pragma unroll
;                 for (int dt = 0; dt < 4; ++dt) o[qt][dt] = o[qt][dt] * alpha; }
;             mrun[qt] = mnew;
;         }
;         bf16x8 pb[2][2];
; #pragma unroll
;         for (int qt = 0; qt < 2; ++qt)
; #pragma unroll
;             for (int p = 0; p < 2; ++p) { u32x4 w; w.x = cvtpk(s[qt][2 * p][0], s[qt][2 * p][1]); w.y = cvtpk(s[qt][2 * p][2], s[qt][2 * p][3]);
;                 w.z = cvtpk(s[qt][2 * p + 1][0], s[qt][2 * p + 1][1]); w.w = cvtpk(s[qt][2 * p + 1][2], s[qt][2 * p + 1][3]); pb[qt][p] = __builtin_bit_cast(bf16x8, w); }
; #pragma unroll
;         for (int dt = 0; dt < 4; ++dt)
; #pragma unroll
;             for (int p = 0; p < 2; ++p) {
; #pragma unroll
;                 for (int qt = 0; qt < 2; ++qt) o[qt][dt] = MFMA16(vfr[dt][p], pb[qt][p], o[qt][dt]); }
;         }
;         LDS_BARRIER();
;         kb = kbn; kbn = kbnn; buf ^= 1;
.LBB0_159:
	v_add_f32_e32 v129, v160, v161
	v_add_f32_e32 v130, v162, v163
	v_exp_f32_e32 v175, v200
	v_add_f32_e32 v129, v129, v130
	v_add_f32_e32 v130, v164, v165
	v_add_f32_e32 v131, v166, v167
	v_add_f32_e32 v129, 0, v129
	v_add_f32_e32 v130, v130, v131
	v_add_f32_e32 v129, v130, v129
	v_add_f32_e32 v130, v168, v169
	v_add_f32_e32 v131, v170, v171
	v_add_f32_e32 v130, v130, v131
	v_add_f32_e32 v129, v130, v129
	v_add_f32_e32 v130, v172, v173
	v_add_f32_e32 v131, v175, v174
	v_add_f32_e32 v130, v130, v131
	v_add_f32_e32 v129, v130, v129
	v_fmac_f32_e32 v129, v1, v128
	v_add_f32_e32 v1, v144, v145
	v_add_f32_e32 v130, v146, v147
	v_exp_f32_e32 v128, v197
	v_add_f32_e32 v1, v1, v130
	v_add_f32_e32 v130, v148, v149
	v_add_f32_e32 v131, v150, v151
	v_add_f32_e32 v1, 0, v1
	v_add_f32_e32 v130, v130, v131
	v_add_f32_e32 v1, v130, v1
	v_add_f32_e32 v130, v152, v153
	v_add_f32_e32 v131, v154, v155
	v_add_f32_e32 v130, v130, v131
	v_add_f32_e32 v1, v130, v1
	v_add_f32_e32 v130, v156, v157
	v_add_f32_e32 v131, v128, v158
	v_add_f32_e32 v130, v130, v131
	v_add_f32_e32 v1, v130, v1
	v_cvt_pk_bf16_f32 v130, v144, v145
	v_cvt_pk_bf16_f32 v131, v146, v147
	v_cvt_pk_bf16_f32 v132, v148, v149
	v_cvt_pk_bf16_f32 v133, v150, v151
	v_cvt_pk_bf16_f32 v138, v160, v161
	v_cvt_pk_bf16_f32 v139, v162, v163
	v_cvt_pk_bf16_f32 v140, v164, v165
	v_cvt_pk_bf16_f32 v141, v166, v167
	s_waitcnt lgkmcnt(11)
	v_mfma_f32_16x16x32_bf16 v[68:71], v[124:127], v[130:133], v[68:71]
	v_cvt_pk_bf16_f32 v134, v152, v153
	v_cvt_pk_bf16_f32 v135, v154, v155
	v_cvt_pk_bf16_f32 v136, v156, v157
	v_mfma_f32_16x16x32_bf16 v[52:55], v[124:127], v[138:141], v[52:55]
	v_cvt_pk_bf16_f32 v137, v158, v128
	v_cvt_pk_bf16_f32 v142, v168, v169
	v_cvt_pk_bf16_f32 v143, v170, v171
	s_waitcnt lgkmcnt(10)
	v_mfma_f32_16x16x32_bf16 v[64:67], v[116:119], v[130:133], v[64:67]
	v_cvt_pk_bf16_f32 v144, v172, v173
	v_cvt_pk_bf16_f32 v145, v174, v175
	s_and_b64 s[0:1], exec, s[8:9]
	v_mfma_f32_16x16x32_bf16 v[48:51], v[116:119], v[138:141], v[48:51]
	s_cselect_b32 s0, -1, s46
	s_cmp_lg_u32 m0, 0
	s_cbranch_scc1 .Lstg2_end
	s_waitcnt lgkmcnt(0)
	s_barrier
.Lstg2_end:
	s_lshl_b32 s1, 1, s0
	s_waitcnt lgkmcnt(9)
	v_mfma_f32_16x16x32_bf16 v[60:63], v[108:111], v[130:133], v[60:63]
	v_fmac_f32_e32 v1, v195, v2
	s_andn2_b32 s41, s41, s1
	s_xor_b32 s45, s45, 1
	v_mfma_f32_16x16x32_bf16 v[44:47], v[108:111], v[138:141], v[44:47]
	s_andn2_b64 vcc, exec, s[6:7]
	s_waitcnt lgkmcnt(8)
	v_mfma_f32_16x16x32_bf16 v[56:59], v[100:103], v[130:133], v[56:59]
	v_mfma_f32_16x16x32_bf16 v[40:43], v[100:103], v[138:141], v[40:43]
	s_waitcnt lgkmcnt(3)
	v_mfma_f32_16x16x32_bf16 v[68:71], v[120:123], v[134:137], v[68:71]
	v_mfma_f32_16x16x32_bf16 v[52:55], v[120:123], v[142:145], v[52:55]
	s_waitcnt lgkmcnt(2)
	v_mfma_f32_16x16x32_bf16 v[64:67], v[112:115], v[134:137], v[64:67]
	v_mfma_f32_16x16x32_bf16 v[48:51], v[112:115], v[142:145], v[48:51]
	s_waitcnt lgkmcnt(1)
	v_mfma_f32_16x16x32_bf16 v[60:63], v[104:107], v[134:137], v[60:63]
	v_mfma_f32_16x16x32_bf16 v[44:47], v[104:107], v[142:145], v[44:47]
	s_waitcnt lgkmcnt(0)
	v_mfma_f32_16x16x32_bf16 v[56:59], v[96:99], v[134:137], v[56:59]
	v_mfma_f32_16x16x32_bf16 v[40:43], v[96:99], v[142:145], v[40:43]
	s_cbranch_vccz .LBB0_47
	v_mov_b32_e32 v195, v1
	v_mov_b32_e32 v1, v129
	v_mov_b32_e32 v200, v3
	v_mov_b32_e32 v196, v159
	s_mov_b32 s10, s13
	s_mov_b32 s13, s0
	s_cmp_lt_i32 s13, 0
	s_cselect_b64 s[6:7], -1, 0
	s_and_b64 vcc, exec, s[6:7]
	s_cbranch_vccz .LBB0_148
	s_branch .LBB0_149
